# NSA top-n ranking scan bounded at the current (last valid) block; hazard nops restored in gather token prologue
# speedup vs baseline: 1.0123x; 1.0123x over previous
; __device__ void peer_gather_phase(const Params& P, int l, bool do_store) {
;     ...
;   for (int r4 = blockIdx.x; r4 < T_TOK / 4; r4 += gridDim.x) {
;     const int t = r4 * 4 + w;
;     f32x2 xf[8];
;     const int ev0 = nev0, ev1 = nev1; const float gv0 = ngv0, gv1 = ngv1;
;     {
;       const uint4 xa = nxa, xc = nxc;
;       xf[0] = f32x2{lo_f(xa.x), hi_f(xa.x)}; xf[1] = f32x2{lo_f(xa.y), hi_f(xa.y)}; xf[2] = f32x2{lo_f(xa.z), hi_f(xa.z)}; xf[3] = f32x2{lo_f(xa.w), hi_f(xa.w)};
;       xf[4] = f32x2{lo_f(xc.x), hi_f(xc.x)}; xf[5] = f32x2{lo_f(xc.y), hi_f(xc.y)}; xf[6] = f32x2{lo_f(xc.z), hi_f(xc.z)}; xf[7] = f32x2{lo_f(xc.w), hi_f(xc.w)};
;     }
;     f32x2 xu[16];
;     {
;       const bf16_t* xq = P.XB + (size_t)t * 1024 + (lane & 31) * 32;
;       const uint4 q0 = *(const uint4*)xq, q1 = *(const uint4*)(xq + 8), q2 = *(const uint4*)(xq + 16), q3 = *(const uint4*)(xq + 24);
;       xu[0] = f32x2{lo_f(q0.x), hi_f(q0.x)}; xu[1] = f32x2{lo_f(q0.y), hi_f(q0.y)}; xu[2] = f32x2{lo_f(q0.z), hi_f(q0.z)}; xu[3] = f32x2{lo_f(q0.w), hi_f(q0.w)};
;       xu[4] = f32x2{lo_f(q1.x), hi_f(q1.x)}; xu[5] = f32x2{lo_f(q1.y), hi_f(q1.y)}; xu[6] = f32x2{lo_f(q1.z), hi_f(q1.z)}; xu[7] = f32x2{lo_f(q1.w), hi_f(q1.w)};
;       xu[8] = f32x2{lo_f(q2.x), hi_f(q2.x)}; xu[9] = f32x2{lo_f(q2.y), hi_f(q2.y)}; xu[10] = f32x2{lo_f(q2.z), hi_f(q2.z)}; xu[11] = f32x2{lo_f(q2.w), hi_f(q2.w)};
;       xu[12] = f32x2{lo_f(q3.x), hi_f(q3.x)}; xu[13] = f32x2{lo_f(q3.y), hi_f(q3.y)}; xu[14] = f32x2{lo_f(q3.z), hi_f(q3.z)}; xu[15] = f32x2{lo_f(q3.w), hi_f(q3.w)};
;     }
;     f32x2 y[8];
; #pragma unroll
;     for (int k = 0; k < 8; ++k) y[k] = f32x2{0.f, 0.f};
;     {
;       const int r4n = (r4 + (int)gridDim.x < T_TOK / 4) ? r4 + (int)gridDim.x : r4;
;       const int tn = r4n * 4 + w;
;       nev0 = P.EXP[(size_t)tn * 128 + lane]; nev1 = P.EXP[(size_t)tn * 128 + 64 + lane];
;       ngv0 = P.GATE[(size_t)tn * 128 + lane]; ngv1 = P.GATE[(size_t)tn * 128 + 64 + lane];
;       const bf16_t* xbn = P.XB + (size_t)tn * 1024 + lane * 16;
;       nxa = *(const uint4*)xbn; nxc = *(const uint4*)(xbn + 8);
;     }
;     const float sux0 = SU[ev0], sux1 = SU[ev1];
;     const float gsx0 = gv0 * SV[ev0], gsx1 = gv1 * SV[ev1];
;     const bool uphi = (lane >= 32);
;     uint2 uA[12], uB[12]; uint2 vA[8], vB[8];
;     auto load_batch = [&](uint2 (&u6)[12], uint2 (&v8)[8], int bt) {
.LBB0_21:
	v_readlane_b32 s4, v248, 34
	s_mov_b32 s0, s2
	s_add_i32 s2, s2, s4
	s_cmpk_gt_i32 s2, 0x1fff
	s_cselect_b64 s[44:45], -1, 0
	s_cmpk_lt_i32 s2, 0x2000
	v_lshl_add_u32 v16, s0, 2, v73
	s_cselect_b32 s0, s2, s0
	v_lshl_add_u32 v18, s0, 2, v73
	v_ashrrev_i32_e32 v17, 31, v16
	v_readlane_b32 s5, v248, 35
	v_ashrrev_i32_e32 v19, 31, v18
	v_lshlrev_b64 v[0:1], 11, v[16:17]
	v_lshlrev_b64 v[20:21], 9, v[18:19]
	v_readlane_b32 s4, v251, 2
	s_waitcnt vmcnt(1)
	v_mov_b32_e32 v90, v188
	s_waitcnt vmcnt(0)
	v_mov_b32_e32 v92, v179
	v_lshl_add_u64 v[88:89], s[28:29], 0, v[0:1]
	v_lshl_or_b32 v20, v72, 2, v20
	v_readlane_b32 s6, v251, 4
	v_readlane_b32 s7, v251, 5
	v_lshlrev_b64 v[18:19], 11, v[18:19]
	v_mov_b32_e32 v28, v93
	v_mov_b32_e32 v29, v91
	v_lshl_add_u64 v[12:13], v[88:89], 0, v[86:87]
	v_lshl_add_u64 v[22:23], s[6:7], 0, v[20:21]
	v_lshl_add_u64 v[18:19], v[78:79], 0, v[18:19]
	v_ashrrev_i32_e32 v93, 31, v92
	v_readlane_b32 s0, v249, 45
	v_ashrrev_i32_e32 v91, 31, v90
	global_load_dwordx4 v[0:3], v[12:13], off offset:48
	global_load_dwordx4 v[4:7], v[12:13], off offset:32
	global_load_dwordx4 v[8:11], v[12:13], off offset:16
	s_nop 0
	global_load_dwordx4 v[12:15], v[12:13], off
	s_nop 0
	global_load_dword v179, v[22:23], off
	global_load_dword v188, v[22:23], off offset:256
	global_load_dwordx4 v[56:59], v[18:19], off offset:16
	global_load_dwordx4 v[60:63], v[18:19], off
	v_lshlrev_b64 v[18:19], 2, v[92:93]
	v_readlane_b32 s1, v249, 46
	v_lshlrev_b64 v[24:25], 2, v[90:91]
	s_nop 0
	v_lshl_add_u64 v[22:23], s[0:1], 0, v[18:19]
	v_lshl_add_u64 v[26:27], s[0:1], 0, v[24:25]
	v_readlane_b32 s0, v249, 47
	v_readlane_b32 s1, v249, 48
	global_load_dword v189, v[22:23], off
	global_load_dword v190, v[26:27], off
	v_lshl_add_u64 v[18:19], s[0:1], 0, v[18:19]
	v_lshl_add_u64 v[22:23], s[0:1], 0, v[24:25]
	global_load_dword v24, v[18:19], off
	s_nop 0
	global_load_dword v22, v[22:23], off
	v_readlane_b32 s5, v251, 3
	v_mov_b32_e32 v130, 0
	s_nop 0
	v_lshl_add_u64 v[20:21], s[4:5], 0, v[20:21]
	v_readlane_b32 s62, v249, 41
	v_readlane_b32 s63, v249, 42
	v_readlane_b32 s64, v249, 43
	v_readlane_b32 s65, v249, 44
	v_and_b32_e32 v195, 31, v72
	v_mul_u32_u24_e32 v195, 24, v195
	v_lshlrev_b32_e32 v227, 3, v72
	v_readlane_b32 s46, v92, 0
	v_readlane_b32 s47, v92, 1
	v_readlane_b32 s48, v92, 2
	v_readlane_b32 s49, v92, 3
	v_readlane_b32 s50, v92, 4
	v_readlane_b32 s51, v92, 5
	v_readlane_b32 s52, v92, 6
	v_readlane_b32 s53, v92, 7
	v_readlane_b32 s54, v92, 8
	v_readlane_b32 s55, v92, 9
	v_readlane_b32 s56, v92, 10
	v_readlane_b32 s57, v92, 11
	v_readlane_b32 s58, v92, 12
	v_readlane_b32 s59, v92, 13
	v_readlane_b32 s60, v92, 14
	v_readlane_b32 s61, v92, 15
	s_mul_i32 s0, s46, 0x300
	s_mul_i32 s1, s47, 0x300
	v_add_u32_e32 v167, s0, v195
	s_and_saveexec_b64 s[98:99], s[40:41]
	v_add_u32_e32 v167, s1, v195
	s_mov_b64 exec, s[98:99]
	global_load_dwordx2 v[54:55], v167, s[62:63] offset:16
	global_load_dwordx4 v[50:53], v167, s[62:63]
	s_mul_i32 s0, s48, 0x300
	s_mul_i32 s1, s49, 0x300
	v_add_u32_e32 v167, s0, v195
	s_and_saveexec_b64 s[98:99], s[40:41]
	v_add_u32_e32 v167, s1, v195
	s_mov_b64 exec, s[98:99]
	global_load_dwordx2 v[48:49], v167, s[62:63] offset:16
	global_load_dwordx4 v[44:47], v167, s[62:63]
	s_mul_i32 s0, s50, 0x300
	s_mul_i32 s1, s51, 0x300
	v_add_u32_e32 v167, s0, v195
	s_and_saveexec_b64 s[98:99], s[40:41]
	v_add_u32_e32 v167, s1, v195
	s_mov_b64 exec, s[98:99]
	global_load_dwordx2 v[42:43], v167, s[62:63] offset:16
	global_load_dwordx4 v[38:41], v167, s[62:63]
	s_mul_i32 s0, s52, 0x300
	s_mul_i32 s1, s53, 0x300
	v_add_u32_e32 v167, s0, v195
	s_and_saveexec_b64 s[98:99], s[40:41]
	v_add_u32_e32 v167, s1, v195
	s_mov_b64 exec, s[98:99]
	global_load_dwordx2 v[36:37], v167, s[62:63] offset:16
	global_load_dwordx4 v[32:35], v167, s[62:63]
	s_mul_i32 s0, s54, 0x300
	s_mul_i32 s1, s55, 0x300
	v_add_u32_e32 v167, s0, v195
	s_and_saveexec_b64 s[98:99], s[40:41]
	v_add_u32_e32 v167, s1, v195
	s_mov_b64 exec, s[98:99]
	global_load_dwordx2 v[200:201], v167, s[62:63] offset:16
	global_load_dwordx4 v[196:199], v167, s[62:63]
	s_mul_i32 s0, s56, 0x300
	s_mul_i32 s1, s57, 0x300
	v_add_u32_e32 v167, s0, v195
	s_and_saveexec_b64 s[98:99], s[40:41]
	v_add_u32_e32 v167, s1, v195
	s_mov_b64 exec, s[98:99]
	global_load_dwordx2 v[232:233], v167, s[62:63] offset:16
; __device__ void peer_gather_phase(const Params& P, int l, bool do_store) {
;     ...
;       xf[0] = f32x2{lo_f(xa.x), hi_f(xa.x)}; xf[1] = f32x2{lo_f(xa.y), hi_f(xa.y)}; xf[2] = f32x2{lo_f(xa.z), hi_f(xa.z)}; xf[3] = f32x2{lo_f(xa.w), hi_f(xa.w)};
;       xf[4] = f32x2{lo_f(xc.x), hi_f(xc.x)}; xf[5] = f32x2{lo_f(xc.y), hi_f(xc.y)}; xf[6] = f32x2{lo_f(xc.z), hi_f(xc.z)}; xf[7] = f32x2{lo_f(xc.w), hi_f(xc.w)};
;     }
;     f32x2 xu[16];
;     {
;       const bf16_t* xq = P.XB + (size_t)t * 1024 + (lane & 31) * 32;
;       const uint4 q0 = *(const uint4*)xq, q1 = *(const uint4*)(xq + 8), q2 = *(const uint4*)(xq + 16), q3 = *(const uint4*)(xq + 24);
;       xu[0] = f32x2{lo_f(q0.x), hi_f(q0.x)}; xu[1] = f32x2{lo_f(q0.y), hi_f(q0.y)}; xu[2] = f32x2{lo_f(q0.z), hi_f(q0.z)}; xu[3] = f32x2{lo_f(q0.w), hi_f(q0.w)};
;       xu[4] = f32x2{lo_f(q1.x), hi_f(q1.x)}; xu[5] = f32x2{lo_f(q1.y), hi_f(q1.y)}; xu[6] = f32x2{lo_f(q1.z), hi_f(q1.z)}; xu[7] = f32x2{lo_f(q1.w), hi_f(q1.w)};
;       xu[8] = f32x2{lo_f(q2.x), hi_f(q2.x)}; xu[9] = f32x2{lo_f(q2.y), hi_f(q2.y)}; xu[10] = f32x2{lo_f(q2.z), hi_f(q2.z)}; xu[11] = f32x2{lo_f(q2.w), hi_f(q2.w)};
;       xu[12] = f32x2{lo_f(q3.x), hi_f(q3.x)}; xu[13] = f32x2{lo_f(q3.y), hi_f(q3.y)}; xu[14] = f32x2{lo_f(q3.z), hi_f(q3.z)}; xu[15] = f32x2{lo_f(q3.w), hi_f(q3.w)};
;     }
;     f32x2 y[8];
; #pragma unroll
;     for (int k = 0; k < 8; ++k) y[k] = f32x2{0.f, 0.f};
;     {
;       const int r4n = (r4 + (int)gridDim.x < T_TOK / 4) ? r4 + (int)gridDim.x : r4;
;       const int tn = r4n * 4 + w;
;       nev0 = P.EXP[(size_t)tn * 128 + lane]; nev1 = P.EXP[(size_t)tn * 128 + 64 + lane];
;       ngv0 = P.GATE[(size_t)tn * 128 + lane]; ngv1 = P.GATE[(size_t)tn * 128 + 64 + lane];
;       const bf16_t* xbn = P.XB + (size_t)tn * 1024 + lane * 16;
;       nxa = *(const uint4*)xbn; nxc = *(const uint4*)(xbn + 8);
;     }
;     const float sux0 = SU[ev0], sux1 = SU[ev1];
;     const float gsx0 = gv0 * SV[ev0], gsx1 = gv1 * SV[ev1];
;     const bool uphi = (lane >= 32);
;     uint2 uA[12], uB[12]; uint2 vA[8], vB[8];
;     auto load_batch = [&](uint2 (&u6)[12], uint2 (&v8)[8], int bt) {
;       const int evs = (bt < 8) ? ev0 : ev1;
;       const int kb = (bt & 7) * 8;
; #pragma unroll
;       for (int pr = 0; pr < 4; ++pr) {
;         const int ea = __builtin_amdgcn_readlane(evs, kb + 2 * pr), eb = __builtin_amdgcn_readlane(evs, kb + 2 * pr + 1);
	global_load_dwordx4 v[228:231], v167, s[62:63]
	s_mul_i32 s0, s58, 0x300
	s_mul_i32 s1, s59, 0x300
	v_add_u32_e32 v167, s0, v195
	s_and_saveexec_b64 s[98:99], s[40:41]
	v_add_u32_e32 v167, s1, v195
	s_mov_b64 exec, s[98:99]
	global_load_dwordx2 v[238:239], v167, s[62:63] offset:16
	global_load_dwordx4 v[234:237], v167, s[62:63]
	s_mul_i32 s0, s60, 0x300
	s_mul_i32 s1, s61, 0x300
	v_add_u32_e32 v167, s0, v195
	s_and_saveexec_b64 s[98:99], s[40:41]
	v_add_u32_e32 v167, s1, v195
	s_mov_b64 exec, s[98:99]
	global_load_dwordx2 v[244:245], v167, s[62:63] offset:16
	global_load_dwordx4 v[240:243], v167, s[62:63]
	s_lshl_b32 s0, s46, 9
	s_add_u32 s0, s64, s0
	s_addc_u32 s1, s65, 0
	global_load_dwordx2 v[144:145], v227, s[0:1]
	s_lshl_b32 s0, s47, 9
	s_add_u32 s0, s64, s0
	s_addc_u32 s1, s65, 0
	global_load_dwordx2 v[146:147], v227, s[0:1]
	s_lshl_b32 s0, s48, 9
	s_add_u32 s0, s64, s0
	s_addc_u32 s1, s65, 0
	global_load_dwordx2 v[148:149], v227, s[0:1]
	s_lshl_b32 s0, s49, 9
	s_add_u32 s0, s64, s0
	s_addc_u32 s1, s65, 0
	global_load_dwordx2 v[150:151], v227, s[0:1]
	s_lshl_b32 s0, s50, 9
	s_add_u32 s0, s64, s0
	s_addc_u32 s1, s65, 0
	global_load_dwordx2 v[152:153], v227, s[0:1]
	s_lshl_b32 s0, s51, 9
	s_add_u32 s0, s64, s0
	s_addc_u32 s1, s65, 0
	global_load_dwordx2 v[154:155], v227, s[0:1]
	s_lshl_b32 s0, s52, 9
	s_add_u32 s0, s64, s0
	s_addc_u32 s1, s65, 0
	global_load_dwordx2 v[156:157], v227, s[0:1]
	s_lshl_b32 s0, s53, 9
	s_add_u32 s0, s64, s0
	s_addc_u32 s1, s65, 0
	global_load_dwordx2 v[158:159], v227, s[0:1]
	s_lshl_b32 s0, s54, 9
	s_add_u32 s0, s64, s0
	s_addc_u32 s1, s65, 0
	global_load_dwordx2 v[168:169], v227, s[0:1]
	s_lshl_b32 s0, s55, 9
	s_add_u32 s0, s64, s0
	s_addc_u32 s1, s65, 0
	global_load_dwordx2 v[170:171], v227, s[0:1]
	s_lshl_b32 s0, s56, 9
	s_add_u32 s0, s64, s0
	s_addc_u32 s1, s65, 0
	global_load_dwordx2 v[172:173], v227, s[0:1]
	s_lshl_b32 s0, s57, 9
	s_add_u32 s0, s64, s0
	s_addc_u32 s1, s65, 0
	global_load_dwordx2 v[174:175], v227, s[0:1]
	s_lshl_b32 s0, s58, 9
	s_add_u32 s0, s64, s0
	s_addc_u32 s1, s65, 0
	global_load_dwordx2 v[180:181], v227, s[0:1]
	s_lshl_b32 s0, s59, 9
	s_add_u32 s0, s64, s0
	s_addc_u32 s1, s65, 0
	global_load_dwordx2 v[182:183], v227, s[0:1]
	s_lshl_b32 s0, s60, 9
	s_add_u32 s0, s64, s0
	s_addc_u32 s1, s65, 0
	global_load_dwordx2 v[184:185], v227, s[0:1]
	s_lshl_b32 s0, s61, 9
	s_add_u32 s0, s64, s0
	s_addc_u32 s1, s65, 0
	global_load_dwordx2 v[186:187], v227, s[0:1]
	global_load_dword v91, v[20:21], off
	global_load_dword v93, v[20:21], off offset:256
	v_lshlrev_b64 v[94:95], 10, v[16:17]
	s_mov_b32 s6, 0
	s_mov_b32 s4, 7
	v_mov_b32_e32 v131, v130
	v_mov_b32_e32 v138, v130
	v_mov_b32_e32 v139, v130
	v_mov_b32_e32 v140, v130
	v_mov_b32_e32 v141, v130
	v_mov_b32_e32 v142, v130
	v_mov_b32_e32 v143, v130
	v_mov_b32_e32 v128, v130
	v_mov_b32_e32 v129, v130
	v_mov_b32_e32 v132, v130
	v_mov_b32_e32 v133, v130
	v_mov_b32_e32 v134, v130
	v_mov_b32_e32 v135, v130
	v_mov_b32_e32 v136, v130
	v_mov_b32_e32 v137, v130
	s_movk_i32 s42, 0x300
	s_waitcnt vmcnt(45)
	v_lshlrev_b32_e32 v120, 16, v0
	s_waitcnt vmcnt(44)
	v_lshlrev_b32_e32 v112, 16, v4
	s_waitcnt vmcnt(43)
	v_lshlrev_b32_e32 v104, 16, v8
	s_waitcnt vmcnt(42)
	v_lshlrev_b32_e32 v96, 16, v12
	v_and_b32_e32 v97, 0xffff0000, v12
	v_lshlrev_b32_e32 v98, 16, v13
	v_and_b32_e32 v99, 0xffff0000, v13
	v_lshlrev_b32_e32 v100, 16, v14
	v_and_b32_e32 v101, 0xffff0000, v14
	v_lshlrev_b32_e32 v102, 16, v15
	v_and_b32_e32 v103, 0xffff0000, v15
	v_and_b32_e32 v105, 0xffff0000, v8
	v_lshlrev_b32_e32 v106, 16, v9
	v_and_b32_e32 v107, 0xffff0000, v9
	v_lshlrev_b32_e32 v108, 16, v10
	v_and_b32_e32 v109, 0xffff0000, v10
	v_lshlrev_b32_e32 v110, 16, v11
	v_and_b32_e32 v111, 0xffff0000, v11
	v_and_b32_e32 v113, 0xffff0000, v4
	v_lshlrev_b32_e32 v114, 16, v5
	v_and_b32_e32 v115, 0xffff0000, v5
	v_lshlrev_b32_e32 v116, 16, v6
	v_and_b32_e32 v117, 0xffff0000, v6
	v_lshlrev_b32_e32 v118, 16, v7
	v_and_b32_e32 v119, 0xffff0000, v7
	v_and_b32_e32 v121, 0xffff0000, v0
	v_lshlrev_b32_e32 v122, 16, v1
	v_and_b32_e32 v123, 0xffff0000, v1
	v_lshlrev_b32_e32 v124, 16, v2
	v_and_b32_e32 v125, 0xffff0000, v2
	v_lshlrev_b32_e32 v126, 16, v3
	v_and_b32_e32 v127, 0xffff0000, v3
	s_waitcnt vmcnt(35)
	v_mul_f32_e32 v191, v29, v24
	s_waitcnt vmcnt(34)
	v_mul_f32_e32 v192, v28, v22

; __device__ void nsa_item(const Params& P, int l, int item, char* smem) {
;     ...
;       __syncthreads();
;       float mine[8];
; #pragma unroll
;       for (int jj = 0; jj < 8; ++jj) mine[jj] = imp[q2 * 64 + js * 8 + jj];
;       int cnt[8];
; #pragma unroll
;       for (int jj = 0; jj < 8; ++jj) cnt[jj] = 0;
; #pragma unroll 4
;       for (int j2 = 0; j2 < 64; ++j2) {
;         const float v2 = imp[q2 * 64 + j2];
; #pragma unroll
;         for (int jj = 0; jj < 8; ++jj) {
;           const int j = js * 8 + jj;
;           cnt[jj] += ((v2 > mine[jj]) || (v2 == mine[jj] && j2 < j)) ? 1 : 0;
;         }
;       }
.LBB0_176:
	s_or_b64 exec, exec, s[42:43]
	v_lshlrev_b32_e32 v34, 16, v96
	v_lshlrev_b32_e32 v37, 16, v93
	v_mul_f32_e32 v34, 0xbfb8aa3b, v34
	v_lshl_add_u32 v36, v87, 5, v88
	v_mul_f32_e32 v37, 0xbfb8aa3b, v37
	v_exp_f32_e32 v89, v34
	ds_write_b32 v32, v33 offset:28
	s_waitcnt lgkmcnt(0)
	s_barrier
	ds_read_b128 v[32:35], v36
	v_exp_f32_e32 v142, v37
	ds_read_b128 v[36:39], v36 offset:16
	v_mov_b32_e32 v57, v48
	v_mov_b32_e32 v59, v52
	s_waitcnt lgkmcnt(1)
	v_mov_b32_e32 v80, v32
	v_mov_b32_e32 v49, v32
	v_mov_b32_e32 v32, v33
	v_mov_b32_e32 v82, v34
	v_mov_b32_e32 v51, v34
	v_mov_b32_e32 v34, v35
	s_waitcnt lgkmcnt(0)
	v_mov_b32_e32 v84, v36
	v_mov_b32_e32 v53, v36
	v_mov_b32_e32 v36, v37
	v_mov_b32_e32 v86, v38
	v_mov_b32_e32 v55, v38
	v_mov_b32_e32 v38, v39
	v_mov_b32_e32 v61, v54
	v_mov_b32_e32 v63, v56
	v_mov_b32_e32 v81, v58
	v_mov_b32_e32 v83, v60
	v_mov_b32_e32 v85, v62
	s_mov_b32 s2, 1
	s_lshr_b32 s57, s38, 9
	s_add_i32 s57, s57, 1
	s_lshl_b32 s57, s57, 5
	v_writelane_b32 v253, s57, 3
	s_mov_b32 s57, 0
	v_mov_b32_e32 v91, 0
	v_mov_b32_e32 v90, 0
	v_mov_b32_e32 v94, 0
	v_mov_b32_e32 v93, 0
	v_mov_b32_e32 v99, 0
	v_mov_b32_e32 v97, 0
	v_mov_b32_e32 v103, 0
	v_mov_b32_e32 v102, 0
	v_mov_b32_e32 v107, 0
	v_mov_b32_e32 v106, 0
	v_mov_b32_e32 v104, 0
	v_mov_b32_e32 v105, 0
	v_mov_b32_e32 v100, 0
	v_mov_b32_e32 v101, 0
	v_mov_b32_e32 v109, 0
	v_mov_b32_e32 v108, 0
	s_mov_b32 s61, 0
.LBB0_177:
	v_add_u32_e32 v40, s57, v88
	ds_read_b128 v[44:47], v40
	ds_read_b128 v[40:43], v40 offset:16
	v_cmp_lt_u32_e64 s[46:47], s61, v48
	v_cmp_lt_u32_e64 s[48:49], s2, v57
	s_add_i32 s39, s61, 2
	s_waitcnt lgkmcnt(1)
	v_cmp_eq_f32_e64 s[42:43], v44, v80
	v_cmp_eq_f32_e64 s[44:45], v45, v49
	v_cmp_gt_f32_e32 vcc, v45, v49
	v_cmp_gt_f32_e64 s[0:1], v44, v80
	s_and_b64 s[44:45], s[44:45], s[48:49]
	s_and_b64 s[42:43], s[42:43], s[46:47]
	s_or_b64 s[0:1], s[0:1], s[42:43]
	s_or_b64 s[42:43], vcc, s[44:45]
	v_cndmask_b32_e64 v110, 0, 1, s[42:43]
	v_cmp_eq_f32_e64 s[42:43], v44, v32
	v_cmp_eq_f32_e64 s[44:45], v45, v33
	v_cmp_le_u32_e64 s[46:47], s61, v48
	v_cmp_le_u32_e64 s[48:49], s2, v57
	v_cndmask_b32_e64 v111, 0, 1, s[0:1]
	v_cmp_gt_f32_e32 vcc, v45, v33
	v_cmp_gt_f32_e64 s[0:1], v44, v32
	s_and_b64 s[44:45], s[44:45], s[48:49]
	s_and_b64 s[42:43], s[42:43], s[46:47]
	s_or_b64 s[0:1], s[0:1], s[42:43]
	s_or_b64 s[42:43], vcc, s[44:45]
	v_cndmask_b32_e64 v112, 0, 1, s[42:43]
	v_cmp_eq_f32_e64 s[42:43], v44, v82
	v_cmp_eq_f32_e64 s[44:45], v45, v51
	v_cmp_lt_u32_e64 s[46:47], s61, v52
	v_cmp_lt_u32_e64 s[48:49], s2, v59
	v_cndmask_b32_e64 v113, 0, 1, s[0:1]
	v_cmp_gt_f32_e32 vcc, v45, v51
	v_cmp_gt_f32_e64 s[0:1], v44, v82
	s_and_b64 s[44:45], s[44:45], s[48:49]
	s_and_b64 s[42:43], s[42:43], s[46:47]
	s_or_b64 s[0:1], s[0:1], s[42:43]
	s_or_b64 s[42:43], vcc, s[44:45]
	v_cndmask_b32_e64 v114, 0, 1, s[42:43]
	v_cmp_eq_f32_e64 s[42:43], v44, v34
	v_cmp_eq_f32_e64 s[44:45], v45, v35
	v_cmp_lt_u32_e64 s[46:47], s61, v54
	v_cmp_lt_u32_e64 s[48:49], s2, v61
	v_cndmask_b32_e64 v115, 0, 1, s[0:1]
	v_cmp_gt_f32_e32 vcc, v45, v35
	v_cmp_gt_f32_e64 s[0:1], v44, v34
	s_and_b64 s[44:45], s[44:45], s[48:49]
	s_and_b64 s[42:43], s[42:43], s[46:47]
	s_or_b64 s[0:1], s[0:1], s[42:43]
	s_or_b64 s[42:43], vcc, s[44:45]
	v_cndmask_b32_e64 v116, 0, 1, s[42:43]
	v_cmp_eq_f32_e64 s[42:43], v44, v84
	v_cmp_eq_f32_e64 s[44:45], v45, v53
	v_cmp_lt_u32_e64 s[46:47], s61, v56
	v_cmp_lt_u32_e64 s[48:49], s2, v63
	v_cndmask_b32_e64 v118, 0, 1, s[0:1]
	v_cmp_gt_f32_e32 vcc, v45, v53
	v_cmp_gt_f32_e64 s[0:1], v44, v84
	s_and_b64 s[44:45], s[44:45], s[48:49]
	s_and_b64 s[42:43], s[42:43], s[46:47]
	s_or_b64 s[0:1], s[0:1], s[42:43]
	s_or_b64 s[42:43], vcc, s[44:45]
	v_cndmask_b32_e64 v119, 0, 1, s[42:43]
	v_cmp_eq_f32_e64 s[42:43], v44, v36
	v_cmp_eq_f32_e64 s[44:45], v45, v37
	v_cmp_lt_u32_e64 s[46:47], s61, v58
	v_cmp_lt_u32_e64 s[48:49], s2, v81
	v_cndmask_b32_e64 v120, 0, 1, s[0:1]
	v_cmp_gt_f32_e32 vcc, v45, v37
	v_cmp_gt_f32_e64 s[0:1], v44, v36
	s_and_b64 s[44:45], s[44:45], s[48:49]
	s_and_b64 s[42:43], s[42:43], s[46:47]
	s_or_b64 s[0:1], s[0:1], s[42:43]
	s_or_b64 s[42:43], vcc, s[44:45]
	v_cndmask_b32_e64 v121, 0, 1, s[42:43]
	v_cmp_eq_f32_e64 s[42:43], v44, v86
	v_cmp_eq_f32_e64 s[44:45], v45, v55
	v_cmp_lt_u32_e64 s[46:47], s61, v60
	v_cmp_lt_u32_e64 s[48:49], s2, v83
	v_cndmask_b32_e64 v143, 0, 1, s[0:1]
	v_cmp_gt_f32_e32 vcc, v45, v55
	v_cmp_gt_f32_e64 s[0:1], v44, v86
	s_and_b64 s[44:45], s[44:45], s[48:49]
	s_and_b64 s[42:43], s[42:43], s[46:47]
	s_or_b64 s[0:1], s[0:1], s[42:43]
	s_or_b64 s[42:43], vcc, s[44:45]
	v_cndmask_b32_e64 v144, 0, 1, s[42:43]
	v_cmp_eq_f32_e64 s[42:43], v44, v38
	v_cmp_eq_f32_e64 s[44:45], v45, v39
	v_cmp_lt_u32_e64 s[46:47], s61, v62
	v_cmp_lt_u32_e64 s[48:49], s2, v85
	v_cndmask_b32_e64 v145, 0, 1, s[0:1]
	v_cmp_gt_f32_e32 vcc, v45, v39
	v_cmp_gt_f32_e64 s[0:1], v44, v38
	s_and_b64 s[44:45], s[44:45], s[48:49]
	s_and_b64 s[42:43], s[42:43], s[46:47]
	s_or_b64 s[0:1], s[0:1], s[42:43]
	s_or_b64 s[42:43], vcc, s[44:45]
	s_add_i32 s67, s2, 2
	v_cndmask_b32_e64 v45, 0, 1, s[42:43]
	v_cmp_eq_f32_e64 s[42:43], v47, v49
	v_cmp_eq_f32_e64 s[44:45], v46, v80
	v_cmp_lt_u32_e64 s[46:47], s67, v57
	v_cmp_lt_u32_e64 s[48:49], s39, v48
	v_cndmask_b32_e64 v44, 0, 1, s[0:1]
	v_cmp_gt_f32_e32 vcc, v46, v80
	v_cmp_gt_f32_e64 s[0:1], v47, v49
	s_and_b64 s[44:45], s[44:45], s[48:49]
	s_and_b64 s[42:43], s[42:43], s[46:47]
	s_or_b64 s[0:1], s[0:1], s[42:43]
	s_or_b64 vcc, vcc, s[44:45]
	v_addc_co_u32_e32 v91, vcc, v91, v111, vcc
	v_addc_co_u32_e64 v90, vcc, v90, v110, s[0:1]
	v_cmp_eq_f32_e64 s[42:43], v47, v33
	v_cmp_eq_f32_e64 s[44:45], v46, v32
; __device__ void nsa_item(const Params& P, int l, int item, char* smem) {
;     ...
;       for (int j2 = 0; j2 < 64; ++j2) {
;         const float v2 = imp[q2 * 64 + j2];
; #pragma unroll
;         for (int jj = 0; jj < 8; ++jj) {
;           const int j = js * 8 + jj;
;           cnt[jj] += ((v2 > mine[jj]) || (v2 == mine[jj] && j2 < j)) ? 1 : 0;
;         }
;       }
	v_cmp_le_u32_e64 s[46:47], s67, v57
	v_cmp_le_u32_e64 s[48:49], s39, v48
	v_cmp_gt_f32_e32 vcc, v46, v32
	v_cmp_gt_f32_e64 s[0:1], v47, v33
	s_and_b64 s[44:45], s[44:45], s[48:49]
	s_and_b64 s[42:43], s[42:43], s[46:47]
	s_or_b64 s[0:1], s[0:1], s[42:43]
	s_or_b64 vcc, vcc, s[44:45]
	v_addc_co_u32_e32 v94, vcc, v94, v113, vcc
	v_addc_co_u32_e64 v93, vcc, v93, v112, s[0:1]
	v_cmp_eq_f32_e64 s[42:43], v47, v51
	v_cmp_eq_f32_e64 s[44:45], v46, v82
	v_cmp_lt_u32_e64 s[46:47], s67, v59
	v_cmp_lt_u32_e64 s[48:49], s39, v52
	v_cmp_gt_f32_e32 vcc, v46, v82
	v_cmp_gt_f32_e64 s[0:1], v47, v51
	s_and_b64 s[44:45], s[44:45], s[48:49]
	s_and_b64 s[42:43], s[42:43], s[46:47]
	s_or_b64 s[0:1], s[0:1], s[42:43]
	s_or_b64 vcc, vcc, s[44:45]
	v_addc_co_u32_e32 v99, vcc, v99, v115, vcc
	v_addc_co_u32_e64 v97, vcc, v97, v114, s[0:1]
	v_cmp_eq_f32_e64 s[42:43], v47, v35
	v_cmp_eq_f32_e64 s[44:45], v46, v34
	v_cmp_lt_u32_e64 s[46:47], s67, v61
	v_cmp_lt_u32_e64 s[48:49], s39, v54
	v_cmp_gt_f32_e32 vcc, v46, v34
	v_cmp_gt_f32_e64 s[0:1], v47, v35
	s_and_b64 s[44:45], s[44:45], s[48:49]
	s_and_b64 s[42:43], s[42:43], s[46:47]
	s_or_b64 s[0:1], s[0:1], s[42:43]
	s_or_b64 vcc, vcc, s[44:45]
	v_addc_co_u32_e32 v103, vcc, v103, v118, vcc
	v_addc_co_u32_e64 v102, vcc, v102, v116, s[0:1]
	v_cmp_eq_f32_e64 s[42:43], v47, v53
	v_cmp_eq_f32_e64 s[44:45], v46, v84
	v_cmp_lt_u32_e64 s[46:47], s67, v63
	v_cmp_lt_u32_e64 s[48:49], s39, v56
	v_cmp_gt_f32_e32 vcc, v46, v84
	v_cmp_gt_f32_e64 s[0:1], v47, v53
	s_and_b64 s[44:45], s[44:45], s[48:49]
	s_and_b64 s[42:43], s[42:43], s[46:47]
	s_or_b64 s[0:1], s[0:1], s[42:43]
	s_or_b64 vcc, vcc, s[44:45]
	v_addc_co_u32_e32 v107, vcc, v107, v120, vcc
	v_addc_co_u32_e64 v106, vcc, v106, v119, s[0:1]
	v_cmp_eq_f32_e64 s[42:43], v47, v37
	v_cmp_eq_f32_e64 s[44:45], v46, v36
	v_cmp_lt_u32_e64 s[46:47], s67, v81
	v_cmp_lt_u32_e64 s[48:49], s39, v58
	v_cmp_gt_f32_e32 vcc, v46, v36
	v_cmp_gt_f32_e64 s[0:1], v47, v37
	s_and_b64 s[44:45], s[44:45], s[48:49]
	s_and_b64 s[42:43], s[42:43], s[46:47]
	s_or_b64 s[0:1], s[0:1], s[42:43]
	s_or_b64 vcc, vcc, s[44:45]
	v_addc_co_u32_e32 v104, vcc, v104, v143, vcc
	v_addc_co_u32_e64 v105, vcc, v105, v121, s[0:1]
	v_cmp_eq_f32_e64 s[42:43], v47, v55
	v_cmp_eq_f32_e64 s[44:45], v46, v86
	v_cmp_lt_u32_e64 s[46:47], s67, v83
	v_cmp_lt_u32_e64 s[48:49], s39, v60
	v_cmp_gt_f32_e32 vcc, v46, v86
	v_cmp_gt_f32_e64 s[0:1], v47, v55
	s_and_b64 s[44:45], s[44:45], s[48:49]
	s_and_b64 s[42:43], s[42:43], s[46:47]
	s_or_b64 s[0:1], s[0:1], s[42:43]
	s_or_b64 vcc, vcc, s[44:45]
	v_addc_co_u32_e32 v100, vcc, v100, v145, vcc
	v_addc_co_u32_e64 v101, vcc, v101, v144, s[0:1]
	v_cmp_eq_f32_e64 s[42:43], v47, v39
	v_cmp_eq_f32_e64 s[44:45], v46, v38
	v_cmp_lt_u32_e64 s[46:47], s67, v85
	v_cmp_lt_u32_e64 s[48:49], s39, v62
	v_cmp_gt_f32_e32 vcc, v46, v38
	v_cmp_gt_f32_e64 s[0:1], v47, v39
	s_and_b64 s[44:45], s[44:45], s[48:49]
	s_and_b64 s[42:43], s[42:43], s[46:47]
	s_or_b64 s[0:1], s[0:1], s[42:43]
	s_or_b64 vcc, vcc, s[44:45]
	s_add_i32 s39, s61, 4
	s_add_i32 s67, s2, 4
	v_addc_co_u32_e32 v44, vcc, v109, v44, vcc
	v_addc_co_u32_e64 v45, vcc, v108, v45, s[0:1]
	s_waitcnt lgkmcnt(0)
	v_cmp_eq_f32_e64 s[42:43], v41, v49
	v_cmp_eq_f32_e64 s[44:45], v40, v80
	v_cmp_lt_u32_e64 s[46:47], s67, v57
	v_cmp_lt_u32_e64 s[48:49], s39, v48
	v_cmp_gt_f32_e32 vcc, v40, v80
	v_cmp_gt_f32_e64 s[0:1], v41, v49
	s_and_b64 s[44:45], s[44:45], s[48:49]
	s_and_b64 s[42:43], s[42:43], s[46:47]
	s_or_b64 s[0:1], s[0:1], s[42:43]
	s_or_b64 s[42:43], vcc, s[44:45]
	v_cndmask_b32_e64 v112, 0, 1, s[42:43]
	v_cmp_eq_f32_e64 s[42:43], v41, v33
	v_cmp_eq_f32_e64 s[44:45], v40, v32
	v_cmp_le_u32_e64 s[46:47], s67, v57
	v_cmp_le_u32_e64 s[48:49], s39, v48
	v_cndmask_b32_e64 v113, 0, 1, s[0:1]
	v_cmp_gt_f32_e32 vcc, v40, v32
	v_cmp_gt_f32_e64 s[0:1], v41, v33
	s_and_b64 s[44:45], s[44:45], s[48:49]
	s_and_b64 s[42:43], s[42:43], s[46:47]
	s_or_b64 s[0:1], s[0:1], s[42:43]
	s_or_b64 s[42:43], vcc, s[44:45]
	v_cndmask_b32_e64 v110, 0, 1, s[42:43]
	v_cmp_eq_f32_e64 s[42:43], v41, v51
	v_cmp_eq_f32_e64 s[44:45], v40, v82
	v_cmp_lt_u32_e64 s[46:47], s67, v59
	v_cmp_lt_u32_e64 s[48:49], s39, v52
	v_cndmask_b32_e64 v111, 0, 1, s[0:1]
	v_cmp_gt_f32_e32 vcc, v40, v82
	v_cmp_gt_f32_e64 s[0:1], v41, v51
	s_and_b64 s[44:45], s[44:45], s[48:49]
	s_and_b64 s[42:43], s[42:43], s[46:47]
	s_or_b64 s[0:1], s[0:1], s[42:43]
	s_or_b64 s[42:43], vcc, s[44:45]
	v_cndmask_b32_e64 v108, 0, 1, s[42:43]
	v_cmp_eq_f32_e64 s[42:43], v41, v35
	v_cmp_eq_f32_e64 s[44:45], v40, v34
	v_cmp_lt_u32_e64 s[46:47], s67, v61
	v_cmp_lt_u32_e64 s[48:49], s39, v54
	v_cndmask_b32_e64 v109, 0, 1, s[0:1]
	v_cmp_gt_f32_e32 vcc, v40, v34
	v_cmp_gt_f32_e64 s[0:1], v41, v35
	s_and_b64 s[44:45], s[44:45], s[48:49]
	s_and_b64 s[42:43], s[42:43], s[46:47]
	s_or_b64 s[0:1], s[0:1], s[42:43]
	s_or_b64 s[42:43], vcc, s[44:45]
	v_cndmask_b32_e64 v46, 0, 1, s[42:43]
	v_cmp_eq_f32_e64 s[42:43], v41, v53
	v_cmp_eq_f32_e64 s[44:45], v40, v84
	v_cmp_lt_u32_e64 s[46:47], s67, v63
	v_cmp_lt_u32_e64 s[48:49], s39, v56
	v_cndmask_b32_e64 v47, 0, 1, s[0:1]
	v_cmp_gt_f32_e32 vcc, v40, v84
	v_cmp_gt_f32_e64 s[0:1], v41, v53
	s_and_b64 s[44:45], s[44:45], s[48:49]
	s_and_b64 s[42:43], s[42:43], s[46:47]
	s_or_b64 s[0:1], s[0:1], s[42:43]
	s_or_b64 s[42:43], vcc, s[44:45]
	v_cmp_eq_f32_e64 s[44:45], v41, v37
	v_cmp_lt_u32_e64 s[48:49], s67, v81
	v_cndmask_b32_e64 v114, 0, 1, s[42:43]
	v_cndmask_b32_e64 v115, 0, 1, s[0:1]
	v_cmp_gt_f32_e64 s[42:43], v41, v37
	v_cmp_eq_f32_e64 s[46:47], v40, v36
	v_cmp_lt_u32_e64 s[0:1], s39, v58
	s_and_b64 s[44:45], s[44:45], s[48:49]
	v_cmp_gt_f32_e32 vcc, v40, v36
; __device__ void nsa_item(const Params& P, int l, int item, char* smem) {
;     ...
;       for (int j2 = 0; j2 < 64; ++j2) {
;         const float v2 = imp[q2 * 64 + j2];
; #pragma unroll
;         for (int jj = 0; jj < 8; ++jj) {
;           const int j = js * 8 + jj;
;           cnt[jj] += ((v2 > mine[jj]) || (v2 == mine[jj] && j2 < j)) ? 1 : 0;
;         }
;       }
	s_and_b64 s[0:1], s[46:47], s[0:1]
	s_or_b64 s[42:43], s[42:43], s[44:45]
	s_or_b64 s[0:1], vcc, s[0:1]
	v_cndmask_b32_e64 v118, 0, 1, s[42:43]
	v_cmp_eq_f32_e64 s[42:43], v41, v55
	v_cmp_eq_f32_e64 s[44:45], v40, v86
	v_cmp_lt_u32_e64 s[46:47], s67, v83
	v_cmp_lt_u32_e64 s[48:49], s39, v60
	v_cndmask_b32_e64 v116, 0, 1, s[0:1]
	v_cmp_gt_f32_e32 vcc, v40, v86
	v_cmp_gt_f32_e64 s[0:1], v41, v55
	s_and_b64 s[44:45], s[44:45], s[48:49]
	s_and_b64 s[42:43], s[42:43], s[46:47]
	s_or_b64 s[0:1], s[0:1], s[42:43]
	s_or_b64 s[42:43], vcc, s[44:45]
	v_cndmask_b32_e64 v119, 0, 1, s[42:43]
	v_cmp_eq_f32_e64 s[42:43], v41, v39
	v_cmp_eq_f32_e64 s[44:45], v40, v38
	v_cmp_lt_u32_e64 s[46:47], s67, v85
	v_cmp_lt_u32_e64 s[48:49], s39, v62
	v_cndmask_b32_e64 v120, 0, 1, s[0:1]
	v_cmp_gt_f32_e32 vcc, v40, v38
	v_cmp_gt_f32_e64 s[0:1], v41, v39
	s_and_b64 s[44:45], s[44:45], s[48:49]
	s_and_b64 s[42:43], s[42:43], s[46:47]
	s_or_b64 s[0:1], s[0:1], s[42:43]
	s_or_b64 s[42:43], vcc, s[44:45]
	s_add_i32 s39, s2, 6
	s_add_i32 s67, s61, 6
	v_cndmask_b32_e64 v40, 0, 1, s[42:43]
	v_cmp_eq_f32_e64 s[42:43], v42, v80
	v_cmp_eq_f32_e64 s[44:45], v43, v49
	v_cmp_lt_u32_e64 s[46:47], s67, v48
	v_cmp_lt_u32_e64 s[48:49], s39, v57
	v_cndmask_b32_e64 v41, 0, 1, s[0:1]
	v_cmp_gt_f32_e32 vcc, v43, v49
	v_cmp_gt_f32_e64 s[0:1], v42, v80
	s_and_b64 s[44:45], s[44:45], s[48:49]
	s_and_b64 s[42:43], s[42:43], s[46:47]
	s_or_b64 s[0:1], s[0:1], s[42:43]
	s_or_b64 vcc, vcc, s[44:45]
	v_addc_co_u32_e32 v90, vcc, v90, v113, vcc
	v_addc_co_u32_e64 v91, vcc, v91, v112, s[0:1]
	v_cmp_eq_f32_e64 s[42:43], v42, v32
	v_cmp_eq_f32_e64 s[44:45], v43, v33
	v_cmp_le_u32_e64 s[46:47], s67, v48
	v_cmp_le_u32_e64 s[48:49], s39, v57
	v_cmp_gt_f32_e32 vcc, v43, v33
	v_cmp_gt_f32_e64 s[0:1], v42, v32
	s_and_b64 s[44:45], s[44:45], s[48:49]
	s_and_b64 s[42:43], s[42:43], s[46:47]
	s_or_b64 s[0:1], s[0:1], s[42:43]
	s_or_b64 vcc, vcc, s[44:45]
	v_addc_co_u32_e32 v93, vcc, v93, v111, vcc
	v_addc_co_u32_e64 v94, vcc, v94, v110, s[0:1]
	v_cmp_eq_f32_e64 s[42:43], v42, v82
	v_cmp_eq_f32_e64 s[44:45], v43, v51
	v_cmp_lt_u32_e64 s[46:47], s67, v52
	v_cmp_lt_u32_e64 s[48:49], s39, v59
	v_cmp_gt_f32_e32 vcc, v43, v51
	v_cmp_gt_f32_e64 s[0:1], v42, v82
	s_and_b64 s[44:45], s[44:45], s[48:49]
	s_and_b64 s[42:43], s[42:43], s[46:47]
	s_or_b64 s[0:1], s[0:1], s[42:43]
	s_or_b64 vcc, vcc, s[44:45]
	v_addc_co_u32_e32 v97, vcc, v97, v109, vcc
	v_addc_co_u32_e64 v99, vcc, v99, v108, s[0:1]
	v_cmp_eq_f32_e64 s[42:43], v42, v34
	v_cmp_eq_f32_e64 s[44:45], v43, v35
	v_cmp_lt_u32_e64 s[46:47], s67, v54
	v_cmp_lt_u32_e64 s[48:49], s39, v61
	v_cmp_gt_f32_e32 vcc, v43, v35
	v_cmp_gt_f32_e64 s[0:1], v42, v34
	s_and_b64 s[44:45], s[44:45], s[48:49]
	s_and_b64 s[42:43], s[42:43], s[46:47]
	s_or_b64 s[0:1], s[0:1], s[42:43]
	s_or_b64 vcc, vcc, s[44:45]
	v_addc_co_u32_e32 v102, vcc, v102, v47, vcc
	v_addc_co_u32_e64 v103, vcc, v103, v46, s[0:1]
	v_cmp_eq_f32_e64 s[42:43], v42, v84
	v_cmp_eq_f32_e64 s[44:45], v43, v53
	v_cmp_lt_u32_e64 s[46:47], s67, v56
	v_cmp_lt_u32_e64 s[48:49], s39, v63
	v_cmp_gt_f32_e32 vcc, v43, v53
	v_cmp_gt_f32_e64 s[0:1], v42, v84
	s_and_b64 s[44:45], s[44:45], s[48:49]
	s_and_b64 s[42:43], s[42:43], s[46:47]
	s_or_b64 s[0:1], s[0:1], s[42:43]
	s_or_b64 vcc, vcc, s[44:45]
	v_addc_co_u32_e32 v106, vcc, v106, v115, vcc
	v_addc_co_u32_e64 v107, vcc, v107, v114, s[0:1]
	v_cmp_eq_f32_e64 s[42:43], v42, v36
	v_cmp_eq_f32_e64 s[44:45], v43, v37
	v_cmp_lt_u32_e64 s[46:47], s67, v58
	v_cmp_lt_u32_e64 s[48:49], s39, v81
	v_cmp_gt_f32_e32 vcc, v43, v37
	v_cmp_gt_f32_e64 s[0:1], v42, v36
	s_and_b64 s[44:45], s[44:45], s[48:49]
	s_and_b64 s[42:43], s[42:43], s[46:47]
	s_or_b64 s[0:1], s[0:1], s[42:43]
	s_or_b64 vcc, vcc, s[44:45]
	v_addc_co_u32_e32 v105, vcc, v105, v118, vcc
	v_addc_co_u32_e64 v104, vcc, v104, v116, s[0:1]
	v_cmp_eq_f32_e64 s[42:43], v42, v86
	v_cmp_eq_f32_e64 s[44:45], v43, v55
	v_cmp_lt_u32_e64 s[46:47], s67, v60
	v_cmp_lt_u32_e64 s[48:49], s39, v83
	v_cmp_gt_f32_e32 vcc, v43, v55
	v_cmp_gt_f32_e64 s[0:1], v42, v86
	s_and_b64 s[44:45], s[44:45], s[48:49]
	s_and_b64 s[42:43], s[42:43], s[46:47]
	s_or_b64 s[0:1], s[0:1], s[42:43]
	s_or_b64 vcc, vcc, s[44:45]
	v_addc_co_u32_e32 v101, vcc, v101, v120, vcc
	v_addc_co_u32_e64 v100, vcc, v100, v119, s[0:1]
	v_cmp_eq_f32_e64 s[42:43], v42, v38
	v_cmp_eq_f32_e64 s[44:45], v43, v39
	v_cmp_lt_u32_e64 s[46:47], s67, v62
	v_cmp_lt_u32_e64 s[48:49], s39, v85
	v_cmp_gt_f32_e32 vcc, v43, v39
	v_cmp_gt_f32_e64 s[0:1], v42, v38
	s_and_b64 s[44:45], s[44:45], s[48:49]
	s_and_b64 s[42:43], s[42:43], s[46:47]
	s_or_b64 s[0:1], s[0:1], s[42:43]
	s_or_b64 vcc, vcc, s[44:45]
	s_add_i32 s61, s61, 8
	s_add_i32 s2, s2, 8
	s_add_i32 s57, s57, 32
	v_addc_co_u32_e32 v108, vcc, v45, v41, vcc
	v_addc_co_u32_e64 v109, vcc, v44, v40, s[0:1]
	v_readlane_b32 s39, v253, 3
	s_cmp_lg_u32 s57, s39
	s_cbranch_scc1 .LBB0_177
; DEV int kperm(int m) { return (m & 0x13) | ((m & 4) << 1) | ((m & 8) >> 1); }
; __device__ void nsa_item(const Params& P, int l, int item, char* smem) {
;     ...
;       unsigned bits = 0;
; #pragma unroll
;       for (int jj = 0; jj < 8; ++jj) bits |= (cnt[jj] < 16 ? 1u : 0u) << jj;
;       selb[q2 * 8 + js] = (unsigned char)bits;
;     }
;     __syncthreads();
;     const uint2 selw = *(const uint2*)(selb + q * 8);
;     const unsigned long long selmask = (unsigned long long)selw.x | ((unsigned long long)selw.y << 32);
; #pragma unroll
;     for (int i = 0; i < 16; ++i) {
;       yown[((i & 3) + 8 * (i >> 2)) * 32] = gc * co0[i];
;       yown[(32 + (i & 3) + 8 * (i >> 2)) * 32] = gc * co1[i];
;     }
;     const float qs2 = 0.125f * 1.4426950408889634f, slope2 = slope * 1.4426950408889634f;
;     float ss = 0.f;
; #pragma unroll 1
;     for (int br = 0; br < 2; ++br) {
;       AttAcc A;
; #pragma unroll
;       for (int i = 0; i < 16; ++i) { A.o0[i] = 0.f; A.o1[i] = 0.f; }
;       A.m = -1e30f; A.l = 0.f;
;       const bf16_t* Kg = Hb + (br == 0 ? 1792 : 1920) + g * 64;
;       const bf16_t* VTg = (br == 0 ? P.VsT : P.VwT) + (size_t)((b * 2 + g) * 64) * 4096;
;       const int khi = t0 & ~63;
;       const int klo = (br == 0) ? 0 : (((t0 - 512 > 0) ? (t0 - 512) : 0) & ~63);
;       const int ntile = ((khi - klo) >> 6) + 1;
;       const int wlim = (br == 0) ? (1 << 30) : 512;
;       const int srow = tid >> 3, sc8 = (tid & 7) * 8;
;       const int koff = kperm(srow) * 72 + sc8, voff = 4608 + srow * 72 + sc8;
;       const bf16_t* kgp = Kg + (size_t)srow * HS + sc8;
;       const bf16_t* vgp = VTg + (size_t)srow * 4096 + sc8;
;       uint4 rk0, rk1, rv0, rv1;
;       rk0 = *(const uint4*)(kgp + (size_t)khi * HS); rk1 = *(const uint4*)(kgp + (size_t)(khi + 32) * HS);
;       rv0 = *(const uint4*)(vgp + khi); rv1 = *(const uint4*)(vgp + (size_t)32 * 4096 + khi);
;       *(uint4*)(kvs + koff) = rk0; *(uint4*)(kvs + koff + 32 * 72) = rk1;
	v_add_f32_e32 v32, 1.0, v89
	v_div_scale_f32 v33, s[0:1], v32, v32, 1.0
	v_rcp_f32_e32 v34, v33
	v_add_u32_e32 v41, v91, v90
	v_add_u32_e32 v40, v94, v93
	v_lshlrev_b32_e32 v36, 9, v141
	v_fma_f32 v37, -v33, v34, 1.0
	v_fmac_f32_e32 v34, v37, v34
	v_div_scale_f32 v37, vcc, 1.0, v32, 1.0
	v_mul_f32_e32 v38, v37, v34
	v_fma_f32 v39, -v33, v38, v37
	v_fmac_f32_e32 v38, v39, v34
	v_fma_f32 v33, -v33, v38, v37
	v_div_fmas_f32 v33, v33, v34, v38
	v_cmp_gt_u32_e32 vcc, 16, v41
	v_add_u32_e32 v39, v99, v97
	v_div_fixup_f32 v32, v33, v32, 1.0
	v_cndmask_b32_e64 v41, 0, 1, vcc
	v_cmp_gt_u32_e32 vcc, 16, v40
	v_lshlrev_b32_e32 v33, 7, v140
	v_add_u32_e32 v38, v103, v102
	v_cndmask_b32_e64 v40, 0, 2, vcc
	v_cmp_gt_u32_e32 vcc, 16, v39
	v_and_b32_e32 v33, 0xffffe000, v33
	v_lshlrev_b32_e32 v34, 2, v117
	v_add_u32_e32 v37, v107, v106
	v_cndmask_b32_e64 v39, 0, 4, vcc
	v_cmp_gt_u32_e32 vcc, 16, v38
	v_or3_b32 v141, v36, v33, v34
	v_add_u32_e32 v36, v104, v105
	v_cndmask_b32_e64 v38, 0, 8, vcc
	v_cmp_gt_u32_e32 vcc, 16, v37
	v_add_u32_e32 v34, v100, v101
	v_add_u32_e32 v33, v109, v108
	v_cndmask_b32_e64 v37, 0, 16, vcc
	v_cmp_gt_u32_e32 vcc, 16, v36
	v_or_b32_e32 v40, v40, v41
	v_bitop3_b16 v38, v40, v38, v39 bitop3:0xfe
	v_cndmask_b32_e64 v36, 0, 32, vcc
	v_cmp_gt_u32_e32 vcc, 16, v34
	v_bitop3_b16 v36, v38, v36, v37 bitop3:0xfe
	v_mul_f32_e32 v0, v32, v0
	v_cndmask_b32_e64 v34, 0, 64, vcc
	v_cmp_gt_u32_e32 vcc, 16, v33
	v_mul_f32_e32 v1, v32, v1
	v_and_b32_e32 v35, 0xffff0000, v96
	v_cndmask_b32_e32 v33, 0, v217, vcc
	v_bitop3_b16 v33, v36, v33, v34 bitop3:0xfe
	ds_write_b8 v140, v33 offset:33792
	v_lshlrev_b32_e32 v140, 3, v117
	s_waitcnt lgkmcnt(0)
	s_barrier
	ds_read_b64 v[96:97], v140 offset:33792
	v_mul_f32_e32 v16, v32, v16
	ds_write2_b32 v141, v0, v1 offset1:32
	v_mul_f32_e32 v0, v32, v17
	v_add_u32_e32 v143, 0x1000, v141
	ds_write2_b32 v143, v16, v0 offset1:32
	v_mul_f32_e32 v0, v32, v2
	v_mul_f32_e32 v2, v32, v3
	v_mul_f32_e32 v1, v32, v18
	ds_write2_b32 v141, v0, v2 offset0:64 offset1:96
	v_mul_f32_e32 v0, v32, v19
	ds_write2_b32 v143, v1, v0 offset0:64 offset1:96
	v_mul_f32_e32 v0, v32, v4
	v_mul_f32_e32 v2, v32, v5
	v_add_u32_e32 v144, 0x400, v141
	v_mul_f32_e32 v1, v32, v20
	ds_write2_b32 v144, v0, v2 offset1:32
	v_mul_f32_e32 v0, v32, v21
	v_add_u32_e32 v145, 0x1400, v141
	ds_write2_b32 v145, v1, v0 offset1:32
	v_mul_f32_e32 v0, v32, v6
	v_mul_f32_e32 v2, v32, v7
	v_mul_f32_e32 v1, v32, v22
	ds_write2_b32 v144, v0, v2 offset0:64 offset1:96
	v_mul_f32_e32 v0, v32, v23
	ds_write2_b32 v145, v1, v0 offset0:64 offset1:96
	v_mul_f32_e32 v0, v32, v8
	v_mul_f32_e32 v2, v32, v9
	v_add_u32_e32 v146, 0x800, v141
	v_mul_f32_e32 v1, v32, v24
	ds_write2_b32 v146, v0, v2 offset1:32
	v_mul_f32_e32 v0, v32, v25
	v_add_u32_e32 v147, 0x1800, v141
	ds_write2_b32 v147, v1, v0 offset1:32
	v_mul_f32_e32 v0, v32, v10
	v_mul_f32_e32 v2, v32, v11
	v_mul_f32_e32 v1, v32, v26
	ds_write2_b32 v146, v0, v2 offset0:64 offset1:96
	v_mul_f32_e32 v0, v32, v27
	ds_write2_b32 v147, v1, v0 offset0:64 offset1:96
	v_mul_f32_e32 v0, v32, v12
	v_mul_f32_e32 v2, v32, v13
	v_add_u32_e32 v148, 0xc00, v141
	v_mul_f32_e32 v1, v32, v28
	ds_write2_b32 v148, v0, v2 offset1:32
	v_mul_f32_e32 v0, v32, v29
	v_add_u32_e32 v149, 0x1c00, v141
	ds_write2_b32 v149, v1, v0 offset1:32
	v_mul_f32_e32 v0, v32, v14
	v_mul_f32_e32 v2, v32, v15
	v_mul_f32_e32 v1, v32, v30
	ds_write2_b32 v148, v0, v2 offset0:64 offset1:96
	v_mul_f32_e32 v0, v32, v31
	s_lshl_b32 s2, s60, 6
	ds_write2_b32 v149, v1, v0 offset0:64 offset1:96
	s_lshl_b64 s[0:1], s[2:3], 1
	v_lshlrev_b32_e32 v1, 1, v50
	v_lshrrev_b32_e32 v2, 1, v50
	s_add_u32 s42, s98, s0
	v_and_b32_e32 v0, 19, v50
	v_and_b32_e32 v1, 8, v1
	v_and_b32_e32 v2, 4, v2
	s_addc_u32 s43, s99, s1
	v_or3_b32 v0, v0, v1, v2
	s_movk_i32 s44, 0x48
	v_mad_u32_u24 v151, v0, s44, v48
	v_mov_b64_e32 v[0:1], s[42:43]
	s_movk_i32 s39, 0x1030
	v_mad_i64_i32 v[0:1], s[42:43], v50, s39, v[0:1]
	v_mad_u64_u32 v[106:107], s[42:43], v50, s44, v[48:49]
	v_readlane_b32 s42, v248, 37
	v_ashrrev_i32_e32 v51, 31, v50
	s_add_i32 s2, s42, s2
	v_lshlrev_b64 v[104:105], 13, v[50:51]
	s_lshl_b64 s[42:43], s[2:3], 13
	s_mov_b32 s61, s3
	s_lshl_b64 s[0:1], s[62:63], 13
	v_lshl_add_u64 v[108:109], v[104:105], 0, s[42:43]
	s_lshl_b64 s[42:43], s[60:61], 7
	v_mul_f32_e32 v35, 0xbfb8aa3b, v35
	v_lshlrev_b32_e32 v176, 1, v48
	s_add_u32 s42, s5, s42
	v_exp_f32_e32 v150, v35
	v_lshl_add_u64 v[102:103], v[0:1], 0, v[176:177]
	v_mul_u32_u24_e32 v0, 0x48, v117
	s_addc_u32 s43, s6, s43
	v_lshl_add_u32 v153, v0, 1, v98
	v_mov_b64_e32 v[0:1], s[42:43]
	v_mul_f32_e32 v100, 0x3fb8aa3b, v95
	v_mad_i64_i32 v[110:111], s[42:43], v50, s39, v[0:1]
	v_add_u32_e32 v0, s7, v117
	v_lshlrev_b32_e32 v152, 1, v151
	v_lshlrev_b32_e32 v107, 1, v106
	v_mov_b32_e32 v101, v100
	v_lshlrev_b32_e32 v98, 4, v87
	v_mov_b32_e32 v99, v177
	v_sub_u32_e32 v154, v0, v92
	s_mov_b64 s[44:45], 0
	s_mov_b64 s[42:43], -1
	v_mov_b32_e32 v155, 0
	v_lshlrev_b32_e32 v176, 1, v48
	s_movk_i32 s67, 0x110
